# diff loop: separate unmasked-tile fast block (mask selects/prep dropped, exp results and score scaling written directly to final registers)
# speedup vs baseline: 1.1690x; 1.0180x over previous
; DI uint4 gld16(const void* p) { uint4 r; asm volatile("global_load_dwordx4 %0, %1, off" : "=v"(r) : "v"(p) : "memory"); return r; }
; DI void vm_wait0() { asm volatile("s_waitcnt vmcnt(0)" ::: "memory"); }
; DI int crow(int i, int h) { return (i & 3) + 8 * (i >> 2) + 4 * h; }
; #define MFMA32(a, b, c) __builtin_amdgcn_mfma_f32_32x32x16_bf16((a), (b), (c), 0, 0, 0)
; DI void kv_wait(KVRegs& rg) { asm volatile("s_waitcnt vmcnt(0)" : "+v"(rg.k[0]), "+v"(rg.k[1]), "+v"(rg.v[0]), "+v"(rg.v[1]) :: "memory"); }
; template <int DQK>
; DI void attn_tile_step(const bf16_t* sK, const bf16_t* sV, const bf16x8 (&qf)[DQK / 16], int k0, int qpos, int window, float sl2, float& m, float& lsum, f32x16 (&O)[2], int r, int h) {
;     ...
;     for (int ks = 0; ks < NKS; ++ks) { const bf16x8 a = *(const bf16x8*)(sK + (t2 * 32 + r) * LDK + ks * 16 + 8 * h); s[t2] = MFMA32(a, qf[ks], s[t2]); }
;   }
;   float mx = m;
; #pragma unroll
;   for (int t2 = 0; t2 < 2; ++t2)
; #pragma unroll
;     for (int i = 0; i < 16; ++i) { const int kpos = k0 + t2 * 32 + crow(i, h); const bool ok = (kpos <= qpos) && (window == 0 || qpos - kpos < window);
;       const float v = ok ? s[t2][i] * sl2 : -1e30f; s[t2][i] = v; mx = fmaxf(mx, v); }
; DI void diff_item(const Params& p, int l, int b, int hh, int qb, char* smem) {
;     ...
;   for (int kt = 0; kt < kt1; ++kt) {
;     const int k0 = kt * 64;
;     kv_wait(rg); vm_wait0();
;     __syncthreads();
;     kv_commit<32>(rg, sK1, sV); *(uint4*)(sK2 + (tid >> 2) * 40 + (tid & 3) * 8) = rk2;
;     __syncthreads();
;     { const int kn = (kt + 1 < kt1 ? kt + 1 : kt) * 64; kv_issue<32>(K1g, vt, kn, rg); rk2 = gld16(K2g + (size_t)(kn + (tid >> 2)) * LDP + (tid & 3) * 8); }
;     if (k0 > qw0 + 31) continue;
;     attn_tile_step<32>(sK1, sV, qf1, k0, qpos, 0, sl2, m1, l1, O1, r, h);
.LBB0_537:
	s_waitcnt vmcnt(0)
	v_mov_b32_e32 v66, v170
	s_waitcnt vmcnt(0)
	s_barrier
	s_mov_b32 s2, s37
	v_lshlrev_b32_e32 v67, 4, v66
	v_lshrrev_b32_e32 v65, 2, v66
	v_and_b32_e32 v64, 48, v67
	v_mad_u64_u32 v[64:65], s[0:1], v65, s12, v[64:65]
	v_lshrrev_b32_e32 v65, 3, v66
	ds_write_b128 v64, v[112:115]
	v_and_b32_e32 v64, 0x70, v67
	v_mul_lo_u32 v65, v65, s22
	v_add3_u32 v65, v64, v65, s23
	ds_write2_b64 v65, v[120:121], v[122:123] offset1:1
	v_add_u32_e32 v65, 0x100, v66
	s_add_i32 s37, s37, 1
	v_lshrrev_b32_e32 v65, 3, v65
	s_cmp_ge_u32 s37, s36
	v_mul_lo_u32 v65, v65, s22
	s_cselect_b64 s[8:9], -1, 0
	s_cmp_lt_u32 s37, s36
	v_add3_u32 v64, v64, v65, s23
	s_cselect_b32 s0, s37, s2
	v_mov_b32_e32 v70, v170
	ds_write2_b64 v64, v[124:125], v[126:127] offset1:1
	s_lshl_b32 s2, s0, 6
	ds_write_b128 v208, v[116:119] offset:5120
	s_waitcnt lgkmcnt(0)
	s_barrier
	s_movk_i32 s6, 0x1a00
	v_ashrrev_i32_e32 v66, 2, v70
	v_add_u32_e32 v68, s2, v66
	v_mov_b64_e32 v[66:67], s[34:35]
	v_mad_i64_i32 v[66:67], s[4:5], v68, s6, v[66:67]
	v_lshlrev_b32_e32 v68, 4, v70
	s_lshl_b64 s[0:1], s[2:3], 1
	v_and_b32_e32 v142, 48, v68
	s_add_u32 s0, s30, s0
	v_lshl_add_u64 v[66:67], v[66:67], 0, v[142:143]
	s_addc_u32 s1, s31, s1
	v_lshl_add_u64 v[66:67], v[66:67], 0, s[14:15]
	v_and_b32_e32 v142, 0x70, v68
	global_load_dwordx4 v[112:115], v[66:67], off
	v_lshl_add_u64 v[66:67], s[0:1], 0, v[142:143]
	v_ashrrev_i32_e32 v68, 3, v70
	v_mad_i64_i32 v[68:69], s[0:1], v68, s13, v[66:67]
	global_load_dwordx4 v[120:123], v[68:69], off
	v_add_u32_e32 v68, 0x100, v70
	v_ashrrev_i32_e32 v68, 3, v68
	v_add_u32_e32 v64, s2, v204
	v_mad_i64_i32 v[66:67], s[0:1], v68, s13, v[66:67]
	global_load_dwordx4 v[124:127], v[66:67], off
	v_mad_i64_i32 v[64:65], s[4:5], v64, s6, v[148:149]
	global_load_dwordx4 v[116:119], v[64:65], off
	v_cmp_le_i32_e32 vcc, s21, v205
	s_and_saveexec_b64 s[6:7], vcc
	s_cbranch_execz .LBB0_536
	v_readfirstlane_b32 s0, v205
	s_add_i32 s0, s0, -94
	s_cmp_le_i32 s21, s0
	s_cbranch_scc1 .Ldiff_fast
	ds_read_b128 v[64:67], v206
	ds_read_b128 v[80:83], v206 offset:32
	v_cmp_lt_i32_e32 vcc, v180, v179
	v_add_u32_e32 v142, s21, v203
	v_or_b32_e32 v153, 49, v142
	s_waitcnt vmcnt(3) lgkmcnt(1)
	v_mfma_f32_32x32x16_bf16 v[64:79], v[64:67], v[96:99], 0
	v_cndmask_b32_e32 v84, v177, v180, vcc
	v_lshlrev_b32_e32 v152, 2, v84
	v_or_b32_e32 v158, 48, v142
	s_mov_b32 s2, 0x3e8293ee
	v_cmp_gt_i32_e64 s[0:1], v153, v145
	v_cmp_gt_i32_e64 s[38:39], v158, v140
	v_cmp_gt_i32_e64 s[84:85], v140, v142
	s_waitcnt vmcnt(1) lgkmcnt(0)
	v_mfma_f32_32x32x16_bf16 v[64:79], v[80:83], v[104:107], v[64:79]
	ds_read_b128 v[80:83], v206 offset:2560
	ds_read_b128 v[154:157], v206 offset:2592
	v_cmp_gt_i32_e64 s[86:87], v142, v140
	v_add_u32_e32 v209, 0x2800, v207
	ds_read2_b64 v[136:139], v209 offset1:2
	ds_read2_b64 v[132:135], v209 offset0:4 offset1:6
	v_add_u32_e32 v210, 0x3800, v207
	s_nop 4
	v_mul_f32_e32 v159, 0x3e8293ee, v64
	s_waitcnt lgkmcnt(3)
	v_mfma_f32_32x32x16_bf16 v[80:95], v[80:83], v[96:99], 0
	v_mul_f32_e32 v160, 0x3e8293ee, v65
	v_cndmask_b32_e64 v160, v189, v160, s[84:85]
	v_cndmask_b32_e64 v159, v159, v189, s[86:87]
	s_waitcnt lgkmcnt(2)
	v_mfma_f32_32x32x16_bf16 v[80:95], v[154:157], v[104:107], v[80:95]
	s_nop 11
	v_pk_mul_f32 v[64:65], v[88:89], s[2:3] op_sel_hi:[1,0]
	v_or_b32_e32 v88, 51, v142
	v_or_b32_e32 v89, 50, v142
	v_cndmask_b32_e64 v153, v65, v189, s[0:1]
	v_cndmask_b32_e64 v154, v64, v189, s[38:39]
	v_pk_mul_f32 v[64:65], v[90:91], s[2:3] op_sel_hi:[1,0]
	v_cmp_gt_i32_e64 s[40:41], v88, v145
	v_cmp_gt_i32_e64 s[42:43], v89, v140
	v_or_b32_e32 v88, 57, v142
	v_or_b32_e32 v89, 56, v142
	v_cndmask_b32_e64 v156, v65, v189, s[40:41]
	v_cndmask_b32_e64 v158, v64, v189, s[42:43]
	v_pk_mul_f32 v[64:65], v[92:93], s[2:3] op_sel_hi:[1,0]
	v_cmp_gt_i32_e64 s[44:45], v88, v145
	v_cmp_gt_i32_e64 s[46:47], v89, v140
	v_or_b32_e32 v88, 59, v142
	v_or_b32_e32 v89, 58, v142
	v_cndmask_b32_e64 v90, v65, v189, s[44:45]
	v_cndmask_b32_e64 v91, v64, v189, s[46:47]
	v_pk_mul_f32 v[64:65], v[94:95], s[2:3] op_sel_hi:[1,0]
	v_cmp_gt_i32_e64 s[48:49], v88, v145
	v_cmp_gt_i32_e64 s[50:51], v89, v140
	v_or_b32_e32 v92, 33, v142
	v_or_b32_e32 v93, 32, v142
	v_cndmask_b32_e64 v88, v65, v189, s[48:49]
	v_cndmask_b32_e64 v89, v64, v189, s[50:51]
	v_pk_mul_f32 v[64:65], v[80:81], s[2:3] op_sel_hi:[1,0]
	v_cmp_gt_i32_e64 s[52:53], v92, v145
	v_cmp_gt_i32_e64 s[54:55], v93, v140
	v_or_b32_e32 v92, 35, v142
	v_or_b32_e32 v93, 34, v142
	v_cndmask_b32_e64 v80, v65, v189, s[52:53]
	v_cndmask_b32_e64 v81, v64, v189, s[54:55]
	v_pk_mul_f32 v[64:65], v[82:83], s[2:3] op_sel_hi:[1,0]
	v_cmp_gt_i32_e64 s[56:57], v92, v145
	v_cmp_gt_i32_e64 s[58:59], v93, v140
	v_or_b32_e32 v92, 41, v142
	v_or_b32_e32 v93, 40, v142
	v_cndmask_b32_e64 v82, v65, v189, s[56:57]
	v_cndmask_b32_e64 v83, v64, v189, s[58:59]
	v_pk_mul_f32 v[64:65], v[84:85], s[2:3] op_sel_hi:[1,0]
	v_cmp_gt_i32_e64 s[60:61], v92, v145
	v_cmp_gt_i32_e64 s[62:63], v93, v140
	v_or_b32_e32 v92, 43, v142
	v_or_b32_e32 v93, 42, v142
	v_cndmask_b32_e64 v84, v65, v189, s[60:61]
	v_cndmask_b32_e64 v85, v64, v189, s[62:63]
	v_pk_mul_f32 v[64:65], v[86:87], s[2:3] op_sel_hi:[1,0]
	v_cmp_gt_i32_e64 s[64:65], v92, v145
	v_cmp_gt_i32_e64 s[66:67], v93, v140
	v_or_b32_e32 v92, 17, v142
	v_or_b32_e32 v93, 16, v142
	v_cndmask_b32_e64 v86, v65, v189, s[64:65]
	v_cndmask_b32_e64 v87, v64, v189, s[66:67]
	v_pk_mul_f32 v[64:65], v[72:73], s[2:3] op_sel_hi:[1,0]
	v_cmp_gt_i32_e64 s[68:69], v92, v145
	v_cmp_gt_i32_e64 s[70:71], v93, v140
	v_or_b32_e32 v72, 19, v142
	v_or_b32_e32 v73, 18, v142
	v_cndmask_b32_e64 v92, v65, v189, s[68:69]
; DI float fexp2(float x) { return __builtin_amdgcn_exp2f(x); }
; DI int crow(int i, int h) { return (i & 3) + 8 * (i >> 2) + 4 * h; }
; template <int DQK>
; DI void attn_tile_step(const bf16_t* sK, const bf16_t* sV, const bf16x8 (&qf)[DQK / 16], int k0, int qpos, int window, float sl2, float& m, float& lsum, f32x16 (&O)[2], int r, int h) {
;     ...
;     for (int i = 0; i < 16; ++i) { const int kpos = k0 + t2 * 32 + crow(i, h); const bool ok = (kpos <= qpos) && (window == 0 || qpos - kpos < window);
;       const float v = ok ? s[t2][i] * sl2 : -1e30f; s[t2][i] = v; mx = fmaxf(mx, v); }
;   mx = fmaxf(mx, __shfl_xor(mx, 32));
;   const float corr = fexp2(m - mx); m = mx; float ps = 0.f;
; #pragma unroll
;   for (int t2 = 0; t2 < 2; ++t2)
; #pragma unroll
;     for (int i = 0; i < 16; ++i) { const float pv = (s[t2][i] > -1e29f) ? fexp2(s[t2][i] - mx) : 0.f; s[t2][i] = pv; ps += pv; }
;   lsum = lsum * corr + ps;
; #pragma unroll
;   for (int dt = 0; dt < 2; ++dt)
; #pragma unroll
;     for (int i = 0; i < 16; ++i) O[dt][i] *= corr;
;   pv_accum(s, sV, r, h, O);
	v_cndmask_b32_e64 v93, v64, v189, s[70:71]
	v_pk_mul_f32 v[64:65], v[74:75], s[2:3] op_sel_hi:[1,0]
	v_cmp_gt_i32_e64 s[72:73], v72, v145
	v_cmp_gt_i32_e64 s[74:75], v73, v140
	v_or_b32_e32 v72, 25, v142
	v_or_b32_e32 v73, 24, v142
	v_cndmask_b32_e64 v94, v65, v189, s[72:73]
	v_cndmask_b32_e64 v95, v64, v189, s[74:75]
	v_pk_mul_f32 v[64:65], v[76:77], s[2:3] op_sel_hi:[1,0]
	v_cmp_gt_i32_e64 s[76:77], v72, v145
	v_cmp_gt_i32_e64 s[78:79], v73, v140
	v_or_b32_e32 v72, 27, v142
	v_or_b32_e32 v73, 26, v142
	v_cndmask_b32_e64 v155, v65, v189, s[76:77]
	v_cndmask_b32_e64 v157, v64, v189, s[78:79]
	v_pk_mul_f32 v[64:65], v[78:79], s[2:3] op_sel_hi:[1,0]
	v_cmp_gt_i32_e64 s[80:81], v72, v145
	v_cmp_gt_i32_e64 s[82:83], v73, v140
	v_or_b32_e32 v73, 3, v142
	v_or_b32_e32 v74, 2, v142
	v_cndmask_b32_e64 v161, v65, v189, s[80:81]
	v_cndmask_b32_e64 v162, v64, v189, s[82:83]
	v_pk_mul_f32 v[64:65], v[66:67], s[2:3] op_sel_hi:[1,0]
	v_cmp_gt_i32_e64 s[88:89], v73, v145
	v_cmp_gt_i32_e64 s[90:91], v74, v140
	v_max3_f32 v72, v151, v159, v160
	v_cndmask_b32_e64 v163, v65, v189, s[88:89]
	v_cndmask_b32_e64 v164, v64, v189, s[90:91]
	v_max3_f32 v66, v72, v164, v163
	v_or_b32_e32 v67, 9, v142
	v_or_b32_e32 v72, 8, v142
	v_pk_mul_f32 v[64:65], v[68:69], s[2:3] op_sel_hi:[1,0]
	v_cmp_gt_i32_e64 s[92:93], v67, v145
	v_cmp_gt_i32_e64 s[94:95], v72, v140
	v_or_b32_e32 v67, 11, v142
	v_or_b32_e32 v68, 10, v142
	v_cndmask_b32_e64 v165, v65, v189, s[92:93]
	v_cndmask_b32_e64 v166, v64, v189, s[94:95]
	v_pk_mul_f32 v[64:65], v[70:71], s[2:3] op_sel_hi:[1,0]
	v_cmp_gt_i32_e64 s[96:97], v67, v145
	v_cmp_gt_i32_e32 vcc, v68, v140
	v_max3_f32 v66, v66, v166, v165
	v_cndmask_b32_e64 v142, v65, v189, s[96:97]
	v_cndmask_b32_e32 v167, v64, v189, vcc
	v_max3_f32 v64, v66, v167, v142
	v_max3_f32 v64, v64, v93, v92
	v_max3_f32 v64, v64, v95, v94
	v_max3_f32 v64, v64, v157, v155
	v_max3_f32 v64, v64, v162, v161
	v_max3_f32 v64, v64, v81, v80
	v_max3_f32 v64, v64, v83, v82
	v_max3_f32 v64, v64, v85, v84
	v_max3_f32 v64, v64, v87, v86
	v_max3_f32 v64, v64, v154, v153
	v_max3_f32 v64, v64, v158, v156
	v_max3_f32 v64, v64, v91, v90
	v_max3_f32 v168, v64, v89, v88
	ds_bpermute_b32 v169, v152, v168
	ds_read2_b64 v[76:79], v210 offset0:32 offset1:34
	ds_read2_b64 v[72:75], v210 offset0:36 offset1:38
	ds_read2_b64 v[68:71], v209 offset0:8 offset1:10
	ds_read2_b64 v[64:67], v210 offset0:40 offset1:42
	s_waitcnt lgkmcnt(4)
	v_max_f32_e32 v169, v169, v169
	v_max_f32_e32 v211, v168, v169
	v_sub_f32_e32 v168, v151, v211
	v_sub_f32_e32 v151, v160, v211
	v_exp_f32_e32 v151, v151
	v_sub_f32_e32 v169, v159, v211
	v_exp_f32_e32 v169, v169
	v_sub_f32_e32 v216, v164, v211
	v_mov_b32_e32 v160, v151
	v_sub_f32_e32 v159, v163, v211
	v_exp_f32_e32 v159, v159
	v_exp_f32_e32 v216, v216
	v_mov_b32_e32 v169, v169
	v_add_f32_e32 v151, 0, v169
	v_add_f32_e32 v151, v160, v151
	v_mov_b32_e32 v163, v159
	v_sub_f32_e32 v159, v165, v211
	v_exp_f32_e32 v159, v159
	v_mov_b32_e32 v164, v216
	v_sub_f32_e32 v216, v166, v211
	v_exp_f32_e32 v216, v216
	v_add_f32_e32 v151, v164, v151
	v_add_f32_e32 v151, v163, v151
	v_mov_b32_e32 v165, v159
	v_sub_f32_e32 v159, v142, v211
	v_exp_f32_e32 v159, v159
	v_mov_b32_e32 v166, v216
	v_sub_f32_e32 v216, v167, v211
	v_exp_f32_e32 v216, v216
	v_add_f32_e32 v151, v166, v151
	v_add_f32_e32 v151, v165, v151
	v_mov_b32_e32 v217, v159
	v_sub_f32_e32 v159, v93, v211
	v_exp_f32_e32 v159, v159
	v_mov_b32_e32 v167, v216
	v_add_f32_e32 v142, v167, v151
	v_sub_f32_e32 v151, v92, v211
	v_exp_f32_e32 v151, v151
	v_add_f32_e32 v142, v217, v142
	s_nop 0
	v_mov_b32_e32 v92, v151
	v_sub_f32_e32 v151, v94, v211
	v_exp_f32_e32 v151, v151
	s_nop 1
	v_mov_b32_e32 v93, v159
	v_sub_f32_e32 v159, v95, v211
	v_exp_f32_e32 v159, v159
	v_add_f32_e32 v142, v93, v142
	v_mov_b32_e32 v94, v151
	v_sub_f32_e32 v151, v155, v211
	v_exp_f32_e32 v151, v151
	v_add_f32_e32 v142, v92, v142
	s_nop 0
	v_mov_b32_e32 v95, v159
	v_sub_f32_e32 v159, v157, v211
	v_exp_f32_e32 v159, v159
	v_sub_f32_e32 v155, v162, v211
	v_mov_b32_e32 v216, v151
	v_sub_f32_e32 v151, v161, v211
	v_exp_f32_e32 v151, v151
	v_exp_f32_e32 v155, v155
	v_add_f32_e32 v142, v95, v142
	v_add_f32_e32 v142, v94, v142
	s_nop 0
	v_mov_b32_e32 v218, v159
	v_add_f32_e32 v142, v218, v142
	v_add_f32_e32 v142, v216, v142
	v_mov_b32_e32 v161, v151
	v_sub_f32_e32 v151, v81, v211
	v_exp_f32_e32 v151, v151
	v_mov_b32_e32 v162, v155
	v_add_f32_e32 v142, v162, v142
	v_add_f32_e32 v219, v161, v142
	v_sub_f32_e32 v142, v80, v211
	v_exp_f32_e32 v142, v142
	v_sub_f32_e32 v80, v82, v211
	v_exp_f32_e32 v80, v80
	v_mov_b32_e32 v220, v142
	v_sub_f32_e32 v81, v83, v211
	v_exp_f32_e32 v81, v81
	v_mov_b32_e32 v221, v151
	v_exp_f32_e32 v142, v168
	v_mov_b32_e32 v222, v80
	v_sub_f32_e32 v80, v84, v211
	v_exp_f32_e32 v80, v80
	v_mov_b32_e32 v223, v81
	v_sub_f32_e32 v81, v85, v211
	v_exp_f32_e32 v81, v81
	v_pk_mul_f32 v[48:49], v[48:49], v[142:143] op_sel_hi:[1,0]
	v_mov_b32_e32 v84, v80
	v_sub_f32_e32 v80, v86, v211
	v_exp_f32_e32 v80, v80
	v_mov_b32_e32 v85, v81
	v_sub_f32_e32 v81, v87, v211
	v_exp_f32_e32 v81, v81
	v_pk_mul_f32 v[50:51], v[50:51], v[142:143] op_sel_hi:[1,0]
	v_pk_mul_f32 v[52:53], v[52:53], v[142:143] op_sel_hi:[1,0]
	v_mov_b32_e32 v159, v80
	v_sub_f32_e32 v80, v153, v211
	v_exp_f32_e32 v80, v80
	v_mov_b32_e32 v86, v81
	v_sub_f32_e32 v81, v154, v211
	v_exp_f32_e32 v81, v81
	v_pk_mul_f32 v[54:55], v[54:55], v[142:143] op_sel_hi:[1,0]
	v_pk_mul_f32 v[56:57], v[56:57], v[142:143] op_sel_hi:[1,0]
	v_mov_b32_e32 v155, v80
	v_sub_f32_e32 v80, v156, v211
	v_exp_f32_e32 v80, v80
	v_mov_b32_e32 v157, v81
	v_sub_f32_e32 v81, v158, v211
	v_exp_f32_e32 v81, v81
	v_mov_b32_e32 v151, v80
	v_sub_f32_e32 v80, v90, v211
	v_exp_f32_e32 v87, v80
	v_mov_b32_e32 v153, v81
	v_pk_mul_f32 v[58:59], v[58:59], v[142:143] op_sel_hi:[1,0]
	v_pk_mul_f32 v[60:61], v[60:61], v[142:143] op_sel_hi:[1,0]
	v_pk_mul_f32 v[62:63], v[62:63], v[142:143] op_sel_hi:[1,0]
	v_cvt_pk_bf16_f32 v83, v167, v217
	v_cvt_pk_bf16_f32 v82, v166, v165
	v_cvt_pk_bf16_f32 v81, v164, v163
	v_cvt_pk_bf16_f32 v80, v169, v160
	v_pk_mul_f32 v[16:17], v[16:17], v[142:143] op_sel_hi:[1,0]
	v_pk_mul_f32 v[18:19], v[18:19], v[142:143] op_sel_hi:[1,0]
	v_mfma_f32_32x32x16_bf16 v[48:63], v[136:139], v[80:83], v[48:63]
	v_mul_f32_e64 v20, v20, v142
	v_mul_f32_e64 v21, v21, v142
	v_mul_f32_e64 v22, v22, v142
	v_mul_f32_e64 v23, v23, v142
	v_mul_f32_e64 v24, v24, v142
	v_mul_f32_e64 v25, v25, v142
	v_pk_mul_f32 v[26:27], v[26:27], v[142:143] op_sel_hi:[1,0]
	v_pk_mul_f32 v[28:29], v[28:29], v[142:143] op_sel_hi:[1,0]
	v_pk_mul_f32 v[30:31], v[30:31], v[142:143] op_sel_hi:[1,0]
	s_waitcnt lgkmcnt(3)
; DI int crow(int i, int h) { return (i & 3) + 8 * (i >> 2) + 4 * h; }
; #define MFMA32(a, b, c) __builtin_amdgcn_mfma_f32_32x32x16_bf16((a), (b), (c), 0, 0, 0)
; DI void pv_accum(const f32x16 (&s)[2], const bf16_t* sV, int r, int h, f32x16 (&O)[2]) {
;     ...
;       const bf16x8 pf = pack8(s[t2], s2);
; #pragma unroll
;       for (int dt = 0; dt < 2; ++dt) {
;         const bf16_t* vp = sV + (dt * 32 + r) * 68 + t2 * 32 + 16 * s2 + 4 * h;
;         const s16x4 lo = *(const s16x4*)vp, hi = *(const s16x4*)(vp + 8);
;         const bf16x8 vf = __builtin_shufflevector(lo, hi, 0, 1, 2, 3, 4, 5, 6, 7);
;         O[dt] = MFMA32(vf, pf, O[dt]);
; template <int DQK>
; DI void attn_tile_step(const bf16_t* sK, const bf16_t* sV, const bf16x8 (&qf)[DQK / 16], int k0, int qpos, int window, float sl2, float& m, float& lsum, f32x16 (&O)[2], int r, int h) {
;     ...
;     for (int ks = 0; ks < NKS; ++ks) { const bf16x8 a = *(const bf16x8*)(sK + (t2 * 32 + r) * LDK + ks * 16 + 8 * h); s[t2] = MFMA32(a, qf[ks], s[t2]); }
;   }
;   float mx = m;
; #pragma unroll
;   for (int t2 = 0; t2 < 2; ++t2)
; #pragma unroll
;     for (int i = 0; i < 16; ++i) { const int kpos = k0 + t2 * 32 + crow(i, h); const bool ok = (kpos <= qpos) && (window == 0 || qpos - kpos < window);
;       const float v = ok ? s[t2][i] * sl2 : -1e30f; s[t2][i] = v; mx = fmaxf(mx, v); }
	s_nop 0
	v_mfma_f32_32x32x16_bf16 v[16:31], v[76:79], v[80:83], v[16:31]
	v_cvt_pk_bf16_f32 v79, v162, v161
	v_cvt_pk_bf16_f32 v78, v218, v216
	v_cvt_pk_bf16_f32 v77, v95, v94
	v_cvt_pk_bf16_f32 v76, v93, v92
	v_sub_f32_e32 v80, v91, v211
	v_exp_f32_e32 v80, v80
	v_mfma_f32_32x32x16_bf16 v[48:63], v[132:135], v[76:79], v[48:63]
	v_mov_b32_e32 v161, v87
	s_nop 1
	v_mov_b32_e32 v163, v80
	v_sub_f32_e32 v80, v88, v211
	s_waitcnt lgkmcnt(2)
	v_mfma_f32_32x32x16_bf16 v[16:31], v[72:75], v[76:79], v[16:31]
	v_cvt_pk_bf16_f32 v75, v86, v159
	v_cvt_pk_bf16_f32 v74, v85, v84
	v_cvt_pk_bf16_f32 v73, v223, v222
	v_cvt_pk_bf16_f32 v72, v221, v220
	s_waitcnt lgkmcnt(1)
	s_nop 0
	v_mfma_f32_32x32x16_bf16 v[48:63], v[68:71], v[72:75], v[48:63]
	v_exp_f32_e32 v68, v80
	v_sub_f32_e32 v69, v89, v211
	v_exp_f32_e32 v69, v69
	v_mov_b32_e32 v165, v68
	s_waitcnt lgkmcnt(0)
	v_mfma_f32_32x32x16_bf16 v[16:31], v[64:67], v[72:75], v[16:31]
	v_mov_b32_e32 v167, v69
	ds_read2_b64 v[64:67], v209 offset0:12 offset1:14
	v_cvt_pk_bf16_f32 v71, v167, v165
	v_cvt_pk_bf16_f32 v69, v153, v151
	v_cvt_pk_bf16_f32 v68, v157, v155
	ds_read2_b64 v[72:75], v210 offset0:44 offset1:46
	v_cvt_pk_bf16_f32 v70, v163, v161
	s_waitcnt lgkmcnt(1)
	s_nop 0
	v_mfma_f32_32x32x16_bf16 v[48:63], v[64:67], v[68:71], v[48:63]
	v_add_f32_e32 v64, v221, v219
	v_add_f32_e32 v64, v220, v64
	v_add_f32_e32 v64, v223, v64
	v_add_f32_e32 v64, v222, v64
	v_add_f32_e32 v64, v85, v64
	v_add_f32_e32 v64, v84, v64
	v_add_f32_e32 v169, v86, v64
	s_waitcnt lgkmcnt(0)
	v_mfma_f32_32x32x16_bf16 v[16:31], v[72:75], v[68:71], v[16:31]
	ds_read_b128 v[64:67], v206 offset:5120
	ds_read_b128 v[80:83], v206 offset:5152
	s_waitcnt lgkmcnt(1)
	v_mfma_f32_32x32x16_bf16 v[64:79], v[64:67], v[100:103], 0
	s_waitcnt vmcnt(0) lgkmcnt(0)
	v_mfma_f32_32x32x16_bf16 v[64:79], v[80:83], v[108:111], v[64:79]
	ds_read_b128 v[80:83], v206 offset:7680
	ds_read_b128 v[216:219], v206 offset:7712
	ds_read2_b64 v[136:139], v209 offset1:2
	ds_read2_b64 v[132:135], v209 offset0:4 offset1:6
	s_waitcnt lgkmcnt(3)
	v_mfma_f32_32x32x16_bf16 v[80:95], v[80:83], v[100:103], 0
	s_nop 5
	v_mul_f32_e32 v154, 0x3e8293ee, v64
	v_mul_f32_e32 v156, 0x3e8293ee, v65
	v_cndmask_b32_e64 v156, v189, v156, s[84:85]
	v_cndmask_b32_e64 v154, v154, v189, s[86:87]
	s_waitcnt lgkmcnt(2)
	v_mfma_f32_32x32x16_bf16 v[80:95], v[216:219], v[108:111], v[80:95]
	s_nop 11
	v_pk_mul_f32 v[64:65], v[88:89], s[2:3] op_sel_hi:[1,0]
	s_nop 0
	v_cndmask_b32_e64 v88, v65, v189, s[0:1]
	v_cndmask_b32_e64 v89, v64, v189, s[38:39]
	v_pk_mul_f32 v[64:65], v[90:91], s[2:3] op_sel_hi:[1,0]
	s_nop 0
	v_cndmask_b32_e64 v90, v65, v189, s[40:41]
	v_cndmask_b32_e64 v91, v64, v189, s[42:43]
	v_pk_mul_f32 v[64:65], v[92:93], s[2:3] op_sel_hi:[1,0]
	s_nop 0
	v_cndmask_b32_e64 v92, v65, v189, s[44:45]
	v_cndmask_b32_e64 v93, v64, v189, s[46:47]
	v_pk_mul_f32 v[64:65], v[94:95], s[2:3] op_sel_hi:[1,0]
	s_nop 0
	v_cndmask_b32_e64 v94, v65, v189, s[48:49]
	v_cndmask_b32_e64 v95, v64, v189, s[50:51]
	v_pk_mul_f32 v[64:65], v[80:81], s[2:3] op_sel_hi:[1,0]
	s_nop 0
	v_cndmask_b32_e64 v80, v65, v189, s[52:53]
	v_cndmask_b32_e64 v81, v64, v189, s[54:55]
	v_pk_mul_f32 v[64:65], v[82:83], s[2:3] op_sel_hi:[1,0]
	s_nop 0
	v_cndmask_b32_e64 v82, v65, v189, s[56:57]
	v_cndmask_b32_e64 v83, v64, v189, s[58:59]
	v_pk_mul_f32 v[64:65], v[84:85], s[2:3] op_sel_hi:[1,0]
	s_nop 0
	v_cndmask_b32_e64 v84, v65, v189, s[60:61]
	v_cndmask_b32_e64 v85, v64, v189, s[62:63]
	v_pk_mul_f32 v[64:65], v[86:87], s[2:3] op_sel_hi:[1,0]
	s_nop 0
	v_cndmask_b32_e64 v86, v65, v189, s[64:65]
	v_cndmask_b32_e64 v87, v64, v189, s[66:67]
	v_pk_mul_f32 v[64:65], v[72:73], s[2:3] op_sel_hi:[1,0]
	v_max3_f32 v72, v150, v154, v156
	v_cndmask_b32_e64 v158, v65, v189, s[68:69]
	v_cndmask_b32_e64 v160, v64, v189, s[70:71]
	v_pk_mul_f32 v[64:65], v[74:75], s[2:3] op_sel_hi:[1,0]
	s_nop 0
	v_cndmask_b32_e64 v162, v65, v189, s[72:73]
	v_cndmask_b32_e64 v164, v64, v189, s[74:75]
	v_pk_mul_f32 v[64:65], v[76:77], s[2:3] op_sel_hi:[1,0]
	s_nop 0
	v_cndmask_b32_e64 v166, v65, v189, s[76:77]
	v_cndmask_b32_e64 v168, v64, v189, s[78:79]
	v_pk_mul_f32 v[64:65], v[78:79], s[2:3] op_sel_hi:[1,0]
	s_nop 0
	v_cndmask_b32_e64 v216, v65, v189, s[80:81]
	v_cndmask_b32_e64 v217, v64, v189, s[82:83]
	v_pk_mul_f32 v[64:65], v[66:67], s[2:3] op_sel_hi:[1,0]
	s_nop 0
	v_cndmask_b32_e64 v218, v65, v189, s[88:89]
	v_cndmask_b32_e64 v219, v64, v189, s[90:91]
	v_pk_mul_f32 v[64:65], v[68:69], s[2:3] op_sel_hi:[1,0]
	v_max3_f32 v66, v72, v219, v218
	v_cndmask_b32_e64 v220, v65, v189, s[92:93]
	v_cndmask_b32_e64 v221, v64, v189, s[94:95]
	v_pk_mul_f32 v[64:65], v[70:71], s[2:3] op_sel_hi:[1,0]
	v_max3_f32 v66, v66, v221, v220
	v_cndmask_b32_e64 v222, v65, v189, s[96:97]
	v_cndmask_b32_e32 v223, v64, v189, vcc
	v_max3_f32 v64, v66, v223, v222
	v_max3_f32 v64, v64, v160, v158
	v_max3_f32 v64, v64, v164, v162
	v_max3_f32 v64, v64, v168, v166
	v_max3_f32 v64, v64, v217, v216
	v_max3_f32 v64, v64, v81, v80
	v_max3_f32 v64, v64, v83, v82
	v_max3_f32 v64, v64, v85, v84
	v_max3_f32 v64, v64, v87, v86
	v_max3_f32 v64, v64, v89, v88
	v_max3_f32 v64, v64, v91, v90
	v_max3_f32 v64, v64, v93, v92
	v_max3_f32 v224, v64, v95, v94
	ds_bpermute_b32 v152, v152, v224
	ds_read2_b64 v[76:79], v210 offset0:32 offset1:34
	ds_read2_b64 v[72:75], v210 offset0:36 offset1:38
	ds_read2_b64 v[68:71], v209 offset0:8 offset1:10
	ds_read2_b64 v[64:67], v210 offset0:40 offset1:42
	s_waitcnt lgkmcnt(4)
; DI float fexp2(float x) { return __builtin_amdgcn_exp2f(x); }
; #define MFMA32(a, b, c) __builtin_amdgcn_mfma_f32_32x32x16_bf16((a), (b), (c), 0, 0, 0)
; DI void pv_accum(const f32x16 (&s)[2], const bf16_t* sV, int r, int h, f32x16 (&O)[2]) {
;     ...
;       const bf16x8 pf = pack8(s[t2], s2);
; #pragma unroll
;       for (int dt = 0; dt < 2; ++dt) {
;         const bf16_t* vp = sV + (dt * 32 + r) * 68 + t2 * 32 + 16 * s2 + 4 * h;
;         const s16x4 lo = *(const s16x4*)vp, hi = *(const s16x4*)(vp + 8);
;         const bf16x8 vf = __builtin_shufflevector(lo, hi, 0, 1, 2, 3, 4, 5, 6, 7);
;         O[dt] = MFMA32(vf, pf, O[dt]);
; template <int DQK>
; DI void attn_tile_step(const bf16_t* sK, const bf16_t* sV, const bf16x8 (&qf)[DQK / 16], int k0, int qpos, int window, float sl2, float& m, float& lsum, f32x16 (&O)[2], int r, int h) {
;     ...
;       const float v = ok ? s[t2][i] * sl2 : -1e30f; s[t2][i] = v; mx = fmaxf(mx, v); }
;   mx = fmaxf(mx, __shfl_xor(mx, 32));
;   const float corr = fexp2(m - mx); m = mx; float ps = 0.f;
; #pragma unroll
;   for (int t2 = 0; t2 < 2; ++t2)
; #pragma unroll
;     for (int i = 0; i < 16; ++i) { const float pv = (s[t2][i] > -1e29f) ? fexp2(s[t2][i] - mx) : 0.f; s[t2][i] = pv; ps += pv; }
;   lsum = lsum * corr + ps;
; #pragma unroll
;   for (int dt = 0; dt < 2; ++dt)
; #pragma unroll
;     for (int i = 0; i < 16; ++i) O[dt][i] *= corr;
;   pv_accum(s, sV, r, h, O);
	v_max_f32_e32 v152, v152, v152
	v_max_f32_e32 v224, v224, v152
	v_sub_f32_e32 v225, v150, v224
	v_sub_f32_e32 v150, v156, v224
	v_exp_f32_e32 v150, v150
	v_sub_f32_e32 v152, v154, v224
	v_exp_f32_e32 v152, v152
	v_mov_b32_e32 v226, v150
	v_sub_f32_e32 v154, v219, v224
	v_exp_f32_e32 v154, v154
	v_mov_b32_e32 v227, v152
	v_sub_f32_e32 v152, v218, v224
	v_exp_f32_e32 v152, v152
	v_add_f32_e32 v150, 0, v227
	v_add_f32_e32 v150, v226, v150
	v_mov_b32_e32 v218, v152
	v_sub_f32_e32 v152, v220, v224
	v_exp_f32_e32 v152, v152
	s_nop 1
	v_mov_b32_e32 v219, v154
	v_sub_f32_e32 v154, v221, v224
	v_exp_f32_e32 v154, v154
	v_add_f32_e32 v150, v219, v150
	v_add_f32_e32 v150, v218, v150
	v_mov_b32_e32 v220, v152
	v_sub_f32_e32 v152, v222, v224
	v_exp_f32_e32 v152, v152
	s_nop 1
	v_mov_b32_e32 v221, v154
	v_sub_f32_e32 v154, v223, v224
	v_exp_f32_e32 v154, v154
	v_add_f32_e32 v150, v221, v150
	v_add_f32_e32 v150, v220, v150
	v_mov_b32_e32 v222, v152
	v_sub_f32_e32 v152, v158, v224
	v_exp_f32_e32 v152, v152
	s_nop 1
	v_mov_b32_e32 v223, v154
	v_sub_f32_e32 v154, v160, v224
	v_exp_f32_e32 v154, v154
	v_add_f32_e32 v150, v223, v150
	v_add_f32_e32 v150, v222, v150
	v_mov_b32_e32 v228, v152
	v_sub_f32_e32 v152, v162, v224
	v_exp_f32_e32 v152, v152
	s_nop 1
	v_mov_b32_e32 v160, v154
	v_sub_f32_e32 v154, v164, v224
	v_exp_f32_e32 v154, v154
	v_add_f32_e32 v150, v160, v150
	v_add_f32_e32 v150, v228, v150
	v_mov_b32_e32 v162, v152
	v_sub_f32_e32 v152, v166, v224
	v_exp_f32_e32 v152, v152
	s_nop 1
	v_mov_b32_e32 v164, v154
	v_sub_f32_e32 v154, v168, v224
	v_exp_f32_e32 v154, v154
	v_add_f32_e32 v150, v164, v150
	v_add_f32_e32 v150, v162, v150
	v_mov_b32_e32 v166, v152
	v_sub_f32_e32 v152, v216, v224
	v_exp_f32_e32 v152, v152
	s_nop 1
	v_mov_b32_e32 v229, v154
	v_sub_f32_e32 v154, v217, v224
	v_exp_f32_e32 v154, v154
	v_add_f32_e32 v150, v229, v150
	v_add_f32_e32 v150, v166, v150
	v_mov_b32_e32 v216, v152
	v_sub_f32_e32 v152, v80, v224
	v_exp_f32_e32 v152, v152
	s_nop 1
	v_mov_b32_e32 v217, v154
	v_sub_f32_e32 v154, v81, v224
	v_exp_f32_e32 v154, v154
	v_add_f32_e32 v150, v217, v150
	v_add_f32_e32 v150, v216, v150
	v_mov_b32_e32 v230, v152
	v_sub_f32_e32 v81, v82, v224
	v_exp_f32_e32 v81, v81
	v_mov_b32_e32 v231, v154
	v_add_f32_e32 v80, v231, v150
	v_sub_f32_e32 v150, v83, v224
	v_exp_f32_e32 v150, v150
	v_sub_f32_e32 v82, v85, v224
	v_mov_b32_e32 v232, v81
	v_sub_f32_e32 v81, v84, v224
	v_exp_f32_e32 v81, v81
	v_exp_f32_e32 v82, v82
	v_add_f32_e32 v80, v230, v80
	v_mov_b32_e32 v233, v150
	v_add_f32_e32 v80, v233, v80
	v_add_f32_e32 v80, v232, v80
	v_mov_b32_e32 v234, v81
	v_sub_f32_e32 v81, v86, v224
	v_exp_f32_e32 v81, v81
	v_mov_b32_e32 v235, v82
	v_sub_f32_e32 v82, v87, v224
	v_exp_f32_e32 v82, v82
	v_add_f32_e32 v80, v235, v80
	v_add_f32_e32 v80, v234, v80
	v_mov_b32_e32 v158, v81
	v_sub_f32_e32 v81, v89, v224
	v_exp_f32_e32 v81, v81
	v_mov_b32_e32 v86, v82
	v_add_f32_e32 v168, v86, v80
	v_sub_f32_e32 v80, v88, v224
	v_exp_f32_e32 v80, v80
	s_nop 0
	v_mov_b32_e32 v154, v80
	v_sub_f32_e32 v80, v90, v224
	v_exp_f32_e32 v80, v80
	v_mov_b32_e32 v156, v81
	v_sub_f32_e32 v81, v91, v224
	v_exp_f32_e32 v81, v81
	v_mov_b32_e32 v150, v80
	v_sub_f32_e32 v80, v93, v224
	v_exp_f32_e32 v87, v80
	v_exp_f32_e32 v80, v225
	v_mov_b32_e32 v152, v81
	v_sub_f32_e32 v81, v92, v224
	v_exp_f32_e32 v88, v81
	v_mov_b32_e32 v81, v142
	v_pk_mul_f32 v[46:47], v[46:47], v[80:81] op_sel_hi:[1,0]
	v_pk_mul_f32 v[44:45], v[44:45], v[80:81] op_sel_hi:[1,0]
	v_pk_mul_f32 v[42:43], v[42:43], v[80:81] op_sel_hi:[1,0]
	v_pk_mul_f32 v[40:41], v[40:41], v[80:81] op_sel_hi:[1,0]
	v_pk_mul_f32 v[38:39], v[38:39], v[80:81] op_sel_hi:[1,0]
	v_pk_mul_f32 v[36:37], v[36:37], v[80:81] op_sel_hi:[1,0]
	v_pk_mul_f32 v[34:35], v[34:35], v[80:81] op_sel_hi:[1,0]
	v_pk_mul_f32 v[32:33], v[32:33], v[80:81] op_sel_hi:[1,0]
	v_cvt_pk_bf16_f32 v85, v223, v222
	v_cvt_pk_bf16_f32 v84, v221, v220
	v_cvt_pk_bf16_f32 v83, v219, v218
	v_cvt_pk_bf16_f32 v82, v227, v226
	v_pk_mul_f32 v[14:15], v[14:15], v[80:81] op_sel_hi:[1,0]
	v_pk_mul_f32 v[12:13], v[12:13], v[80:81] op_sel_hi:[1,0]
	v_mfma_f32_32x32x16_bf16 v[32:47], v[136:139], v[82:85], v[32:47]
	v_mul_f32_e64 v10, v10, v80
	v_mul_f32_e64 v11, v11, v80
	v_mul_f32_e64 v8, v8, v80
	v_mul_f32_e64 v9, v9, v80
	v_mul_f32_e64 v6, v6, v80
	v_mul_f32_e64 v7, v7, v80
	v_pk_mul_f32 v[4:5], v[4:5], v[80:81] op_sel_hi:[1,0]
	v_pk_mul_f32 v[2:3], v[2:3], v[80:81] op_sel_hi:[1,0]
	v_pk_mul_f32 v[0:1], v[0:1], v[80:81] op_sel_hi:[1,0]
	s_waitcnt lgkmcnt(3)
	s_nop 0
	v_mfma_f32_32x32x16_bf16 v[0:15], v[76:79], v[82:85], v[0:15]
	v_cvt_pk_bf16_f32 v79, v217, v216
	v_cvt_pk_bf16_f32 v78, v229, v166
	v_cvt_pk_bf16_f32 v77, v164, v162
	v_cvt_pk_bf16_f32 v76, v160, v228
	v_sub_f32_e32 v83, v94, v224
	v_sub_f32_e32 v82, v95, v224
	v_mfma_f32_32x32x16_bf16 v[32:47], v[132:135], v[76:79], v[32:47]
	v_exp_f32_e32 v83, v83
	v_exp_f32_e32 v82, v82
	v_mov_b32_e32 v160, v88
	s_nop 1
	v_mov_b32_e32 v162, v87
	s_waitcnt lgkmcnt(2)
	v_mfma_f32_32x32x16_bf16 v[0:15], v[72:75], v[76:79], v[0:15]
	v_cvt_pk_bf16_f32 v75, v86, v158
	v_cvt_pk_bf16_f32 v74, v235, v234
	v_cvt_pk_bf16_f32 v73, v233, v232
	v_cvt_pk_bf16_f32 v72, v231, v230
	s_waitcnt lgkmcnt(1)
	s_nop 0
	v_mfma_f32_32x32x16_bf16 v[32:47], v[68:71], v[72:75], v[32:47]
	v_mov_b32_e32 v164, v83
	v_add_f32_e64 v68, v158, v168
	v_add_f32_e64 v69, v159, v169
	v_mov_b32_e32 v166, v82
	v_pk_add_f32 v[68:69], v[156:157], v[68:69]
	v_pk_add_f32 v[76:77], v[154:155], v[68:69]
	s_waitcnt lgkmcnt(0)
	v_mfma_f32_32x32x16_bf16 v[0:15], v[64:67], v[72:75], v[0:15]
	ds_read2_b64 v[64:67], v209 offset0:12 offset1:14
	v_cvt_pk_bf16_f32 v71, v166, v164
	v_cvt_pk_bf16_f32 v69, v152, v150
	v_cvt_pk_bf16_f32 v68, v156, v154
	ds_read2_b64 v[72:75], v210 offset0:44 offset1:46
	v_cvt_pk_bf16_f32 v70, v162, v160
	s_waitcnt lgkmcnt(1)
	s_nop 0
	v_mfma_f32_32x32x16_bf16 v[32:47], v[64:67], v[68:71], v[32:47]
	v_add_f32_e64 v64, v152, v76
	v_add_f32_e64 v65, v153, v77
	v_add_f32_e64 v64, v150, v64
	v_add_f32_e64 v65, v151, v65
	v_add_f32_e64 v64, v162, v64
	v_add_f32_e64 v65, v163, v65
	v_pk_add_f32 v[64:65], v[160:161], v[64:65]
	s_waitcnt lgkmcnt(0)
	v_mfma_f32_32x32x16_bf16 v[0:15], v[72:75], v[68:71], v[0:15]
	v_add_f32_e64 v64, v166, v64
	v_add_f32_e64 v65, v167, v65
	v_add_f32_e64 v64, v164, v64
	v_add_f32_e64 v65, v165, v65
	v_fma_f32 v146, v146, v80, v64
	v_fma_f32 v147, v147, v81, v65
	v_mov_b32_e32 v151, v211
	v_mov_b32_e32 v150, v224
	s_branch .LBB0_536
; DI float fexp2(float x) { return __builtin_amdgcn_exp2f(x); }
; DI int crow(int i, int h) { return (i & 3) + 8 * (i >> 2) + 4 * h; }
; #define MFMA32(a, b, c) __builtin_amdgcn_mfma_f32_32x32x16_bf16((a), (b), (c), 0, 0, 0)
; template <int DQK>
; DI void attn_tile_step(const bf16_t* sK, const bf16_t* sV, const bf16x8 (&qf)[DQK / 16], int k0, int qpos, int window, float sl2, float& m, float& lsum, f32x16 (&O)[2], int r, int h) {
;     ...
;     for (int ks = 0; ks < NKS; ++ks) { const bf16x8 a = *(const bf16x8*)(sK + (t2 * 32 + r) * LDK + ks * 16 + 8 * h); s[t2] = MFMA32(a, qf[ks], s[t2]); }
;   }
;   float mx = m;
; #pragma unroll
;   for (int t2 = 0; t2 < 2; ++t2)
; #pragma unroll
;     for (int i = 0; i < 16; ++i) { const int kpos = k0 + t2 * 32 + crow(i, h); const bool ok = (kpos <= qpos) && (window == 0 || qpos - kpos < window);
;       const float v = ok ? s[t2][i] * sl2 : -1e30f; s[t2][i] = v; mx = fmaxf(mx, v); }
;   mx = fmaxf(mx, __shfl_xor(mx, 32));
;   const float corr = fexp2(m - mx); m = mx; float ps = 0.f;
; #pragma unroll
;   for (int t2 = 0; t2 < 2; ++t2)
; #pragma unroll
;     for (int i = 0; i < 16; ++i) { const float pv = (s[t2][i] > -1e29f) ? fexp2(s[t2][i] - mx) : 0.f; s[t2][i] = pv; ps += pv; }
;   lsum = lsum * corr + ps;
; #pragma unroll
;   for (int dt = 0; dt < 2; ++dt)
; #pragma unroll
;     for (int i = 0; i < 16; ++i) O[dt][i] *= corr;
;   pv_accum(s, sV, r, h, O);
.Ldiff_fast:
	ds_read_b128 v[64:67], v206
	ds_read_b128 v[80:83], v206 offset:32
	v_cmp_lt_i32_e32 vcc, v180, v179
	v_add_u32_e32 v142, s21, v203
	s_waitcnt vmcnt(3) lgkmcnt(1)
	v_mfma_f32_32x32x16_bf16 v[64:79], v[64:67], v[96:99], 0
	v_cndmask_b32_e32 v84, v177, v180, vcc
	v_lshlrev_b32_e32 v152, 2, v84
	s_mov_b32 s2, 0x3e8293ee
	s_waitcnt vmcnt(1) lgkmcnt(0)
	v_mfma_f32_32x32x16_bf16 v[64:79], v[80:83], v[104:107], v[64:79]
	ds_read_b128 v[80:83], v206 offset:2560
	ds_read_b128 v[154:157], v206 offset:2592
	v_add_u32_e32 v209, 0x2800, v207
	ds_read2_b64 v[136:139], v209 offset1:2
	ds_read2_b64 v[132:135], v209 offset0:4 offset1:6
	v_add_u32_e32 v210, 0x3800, v207
	s_nop 4
	s_nop 0
	v_mul_f32_e32 v159, 0x3e8293ee, v64
	s_waitcnt lgkmcnt(3)
	v_mfma_f32_32x32x16_bf16 v[80:95], v[80:83], v[96:99], 0
	v_mul_f32_e32 v160, 0x3e8293ee, v65
	s_waitcnt lgkmcnt(2)
	v_mfma_f32_32x32x16_bf16 v[80:95], v[154:157], v[104:107], v[80:95]
	s_nop 11
	v_mul_f32_e32 v154, s2, v88
	v_mul_f32_e32 v153, s2, v89
	v_mul_f32_e32 v158, s2, v90
	v_mul_f32_e32 v156, s2, v91
	v_mul_f32_e32 v91, s2, v92
	v_mul_f32_e32 v90, s2, v93
	v_mul_f32_e32 v89, s2, v94
	v_mul_f32_e32 v88, s2, v95
	v_pk_mul_f32 v[64:65], v[80:81], s[2:3] op_sel_hi:[1,0]
	v_mov_b32_e32 v80, v65
	v_mov_b32_e32 v81, v64
	v_pk_mul_f32 v[64:65], v[82:83], s[2:3] op_sel_hi:[1,0]
	v_mov_b32_e32 v82, v65
	v_mov_b32_e32 v83, v64
	v_pk_mul_f32 v[64:65], v[84:85], s[2:3] op_sel_hi:[1,0]
	v_mov_b32_e32 v84, v65
	v_mov_b32_e32 v85, v64
	v_pk_mul_f32 v[64:65], v[86:87], s[2:3] op_sel_hi:[1,0]
	v_mov_b32_e32 v86, v65
	v_mov_b32_e32 v87, v64
	v_mul_f32_e32 v93, s2, v72
	v_mul_f32_e32 v92, s2, v73
	v_mul_f32_e32 v95, s2, v74
	v_mul_f32_e32 v94, s2, v75
	v_mul_f32_e32 v157, s2, v76
	v_mul_f32_e32 v155, s2, v77
	v_mul_f32_e32 v162, s2, v78
	v_mul_f32_e32 v161, s2, v79
	v_mul_f32_e32 v164, s2, v66
	v_mul_f32_e32 v163, s2, v67
	v_max3_f32 v72, v151, v159, v160
	v_max3_f32 v66, v72, v164, v163
	v_mul_f32_e32 v166, s2, v68
	v_mul_f32_e32 v165, s2, v69
	v_mul_f32_e32 v167, s2, v70
	v_mul_f32_e32 v142, s2, v71
	v_max3_f32 v66, v66, v166, v165
	v_max3_f32 v64, v66, v167, v142
	v_max3_f32 v64, v64, v93, v92
	v_max3_f32 v64, v64, v95, v94
	v_max3_f32 v64, v64, v157, v155
	v_max3_f32 v64, v64, v162, v161
	v_max3_f32 v64, v64, v81, v80
	v_max3_f32 v64, v64, v83, v82
	v_max3_f32 v64, v64, v85, v84
	v_max3_f32 v64, v64, v87, v86
	v_max3_f32 v64, v64, v154, v153
	v_max3_f32 v64, v64, v158, v156
	v_max3_f32 v64, v64, v91, v90
	v_max3_f32 v168, v64, v89, v88
	ds_bpermute_b32 v169, v152, v168
	ds_read2_b64 v[76:79], v210 offset0:32 offset1:34
	ds_read2_b64 v[72:75], v210 offset0:36 offset1:38
	ds_read2_b64 v[68:71], v209 offset0:8 offset1:10
	ds_read2_b64 v[64:67], v210 offset0:40 offset1:42
	s_waitcnt lgkmcnt(4)
	v_max_f32_e32 v169, v169, v169
	v_max_f32_e32 v211, v168, v169
	v_sub_f32_e32 v168, v151, v211
	v_sub_f32_e32 v151, v160, v211
	v_exp_f32_e32 v160, v151
	v_sub_f32_e32 v169, v159, v211
	v_exp_f32_e32 v169, v169
	v_sub_f32_e32 v216, v164, v211
	v_sub_f32_e32 v159, v163, v211
	v_exp_f32_e32 v163, v159
	v_exp_f32_e32 v164, v216
	v_add_f32_e32 v151, 0, v169
	v_add_f32_e32 v151, v160, v151
	v_sub_f32_e32 v159, v165, v211
	v_exp_f32_e32 v165, v159
	v_sub_f32_e32 v216, v166, v211
	v_exp_f32_e32 v166, v216
	v_add_f32_e32 v151, v164, v151
	v_add_f32_e32 v151, v163, v151
	v_sub_f32_e32 v159, v142, v211
	v_exp_f32_e32 v217, v159
	v_sub_f32_e32 v216, v167, v211
	v_exp_f32_e32 v167, v216
	v_add_f32_e32 v151, v166, v151
	v_add_f32_e32 v151, v165, v151
	v_sub_f32_e32 v159, v93, v211
	v_exp_f32_e32 v93, v159
	v_add_f32_e32 v142, v167, v151
	v_sub_f32_e32 v151, v92, v211
	v_exp_f32_e32 v92, v151
	v_add_f32_e32 v142, v217, v142
	s_nop 0
	v_sub_f32_e32 v151, v94, v211
	v_exp_f32_e32 v94, v151
	s_nop 1
	v_sub_f32_e32 v159, v95, v211
	v_exp_f32_e32 v95, v159
	v_add_f32_e32 v142, v93, v142
	v_sub_f32_e32 v151, v155, v211
	v_exp_f32_e32 v216, v151
	v_add_f32_e32 v142, v92, v142
	s_nop 0
	v_sub_f32_e32 v159, v157, v211
	v_exp_f32_e32 v218, v159
	v_sub_f32_e32 v155, v162, v211
	v_sub_f32_e32 v151, v161, v211
	v_exp_f32_e32 v161, v151
	v_exp_f32_e32 v162, v155
	v_add_f32_e32 v142, v95, v142
	v_add_f32_e32 v142, v94, v142
	s_nop 0
	v_add_f32_e32 v142, v218, v142
	v_add_f32_e32 v142, v216, v142
	v_sub_f32_e32 v151, v81, v211
	v_exp_f32_e32 v221, v151
	v_add_f32_e32 v142, v162, v142
	v_add_f32_e32 v219, v161, v142
	v_sub_f32_e32 v142, v80, v211
	v_exp_f32_e32 v220, v142
	v_sub_f32_e32 v80, v82, v211
	v_exp_f32_e32 v222, v80
	v_sub_f32_e32 v81, v83, v211
	v_exp_f32_e32 v223, v81
	v_exp_f32_e32 v142, v168
	v_sub_f32_e32 v80, v84, v211
	v_exp_f32_e32 v84, v80
	v_sub_f32_e32 v81, v85, v211
	v_exp_f32_e32 v85, v81
	v_pk_mul_f32 v[48:49], v[48:49], v[142:143] op_sel_hi:[1,0]
	v_sub_f32_e32 v80, v86, v211
	v_exp_f32_e32 v159, v80
	v_sub_f32_e32 v81, v87, v211
	v_exp_f32_e32 v86, v81
	v_pk_mul_f32 v[50:51], v[50:51], v[142:143] op_sel_hi:[1,0]
	v_pk_mul_f32 v[52:53], v[52:53], v[142:143] op_sel_hi:[1,0]
	v_sub_f32_e32 v80, v153, v211
	v_exp_f32_e32 v155, v80
	v_sub_f32_e32 v81, v154, v211
	v_exp_f32_e32 v157, v81
	v_pk_mul_f32 v[54:55], v[54:55], v[142:143] op_sel_hi:[1,0]
	v_pk_mul_f32 v[56:57], v[56:57], v[142:143] op_sel_hi:[1,0]
	v_sub_f32_e32 v80, v156, v211
	v_exp_f32_e32 v151, v80
	v_sub_f32_e32 v81, v158, v211
	v_exp_f32_e32 v153, v81
	v_sub_f32_e32 v80, v90, v211
	v_exp_f32_e32 v87, v80
	v_pk_mul_f32 v[58:59], v[58:59], v[142:143] op_sel_hi:[1,0]
	v_pk_mul_f32 v[60:61], v[60:61], v[142:143] op_sel_hi:[1,0]
	v_pk_mul_f32 v[62:63], v[62:63], v[142:143] op_sel_hi:[1,0]
	v_cvt_pk_bf16_f32 v83, v167, v217
	v_cvt_pk_bf16_f32 v82, v166, v165
	v_cvt_pk_bf16_f32 v81, v164, v163
	v_cvt_pk_bf16_f32 v80, v169, v160
	v_pk_mul_f32 v[16:17], v[16:17], v[142:143] op_sel_hi:[1,0]
	v_pk_mul_f32 v[18:19], v[18:19], v[142:143] op_sel_hi:[1,0]
	v_mfma_f32_32x32x16_bf16 v[48:63], v[136:139], v[80:83], v[48:63]
	v_mul_f32_e64 v20, v20, v142
	v_mul_f32_e64 v21, v21, v142
	v_mul_f32_e64 v22, v22, v142
	v_mul_f32_e64 v23, v23, v142
	v_mul_f32_e64 v24, v24, v142
	v_mul_f32_e64 v25, v25, v142
	v_pk_mul_f32 v[26:27], v[26:27], v[142:143] op_sel_hi:[1,0]
	v_pk_mul_f32 v[28:29], v[28:29], v[142:143] op_sel_hi:[1,0]
	v_pk_mul_f32 v[30:31], v[30:31], v[142:143] op_sel_hi:[1,0]
	s_waitcnt lgkmcnt(3)
; DI int crow(int i, int h) { return (i & 3) + 8 * (i >> 2) + 4 * h; }
; #define MFMA32(a, b, c) __builtin_amdgcn_mfma_f32_32x32x16_bf16((a), (b), (c), 0, 0, 0)
; DI void pv_accum(const f32x16 (&s)[2], const bf16_t* sV, int r, int h, f32x16 (&O)[2]) {
;     ...
;       const bf16x8 pf = pack8(s[t2], s2);
; #pragma unroll
;       for (int dt = 0; dt < 2; ++dt) {
;         const bf16_t* vp = sV + (dt * 32 + r) * 68 + t2 * 32 + 16 * s2 + 4 * h;
;         const s16x4 lo = *(const s16x4*)vp, hi = *(const s16x4*)(vp + 8);
;         const bf16x8 vf = __builtin_shufflevector(lo, hi, 0, 1, 2, 3, 4, 5, 6, 7);
;         O[dt] = MFMA32(vf, pf, O[dt]);
; template <int DQK>
; DI void attn_tile_step(const bf16_t* sK, const bf16_t* sV, const bf16x8 (&qf)[DQK / 16], int k0, int qpos, int window, float sl2, float& m, float& lsum, f32x16 (&O)[2], int r, int h) {
;     ...
;     for (int ks = 0; ks < NKS; ++ks) { const bf16x8 a = *(const bf16x8*)(sK + (t2 * 32 + r) * LDK + ks * 16 + 8 * h); s[t2] = MFMA32(a, qf[ks], s[t2]); }
;   }
;   float mx = m;
; #pragma unroll
;   for (int t2 = 0; t2 < 2; ++t2)
; #pragma unroll
;     for (int i = 0; i < 16; ++i) { const int kpos = k0 + t2 * 32 + crow(i, h); const bool ok = (kpos <= qpos) && (window == 0 || qpos - kpos < window);
;       const float v = ok ? s[t2][i] * sl2 : -1e30f; s[t2][i] = v; mx = fmaxf(mx, v); }
	s_nop 0
	v_mfma_f32_32x32x16_bf16 v[16:31], v[76:79], v[80:83], v[16:31]
	v_cvt_pk_bf16_f32 v79, v162, v161
	v_cvt_pk_bf16_f32 v78, v218, v216
	v_cvt_pk_bf16_f32 v77, v95, v94
	v_cvt_pk_bf16_f32 v76, v93, v92
	v_sub_f32_e32 v80, v91, v211
	v_exp_f32_e32 v163, v80
	v_mfma_f32_32x32x16_bf16 v[48:63], v[132:135], v[76:79], v[48:63]
	v_mov_b32_e32 v161, v87
	s_nop 1
	v_sub_f32_e32 v80, v88, v211
	s_waitcnt lgkmcnt(2)
	v_mfma_f32_32x32x16_bf16 v[16:31], v[72:75], v[76:79], v[16:31]
	v_cvt_pk_bf16_f32 v75, v86, v159
	v_cvt_pk_bf16_f32 v74, v85, v84
	v_cvt_pk_bf16_f32 v73, v223, v222
	v_cvt_pk_bf16_f32 v72, v221, v220
	s_waitcnt lgkmcnt(1)
	s_nop 0
	v_mfma_f32_32x32x16_bf16 v[48:63], v[68:71], v[72:75], v[48:63]
	v_exp_f32_e32 v165, v80
	v_sub_f32_e32 v69, v89, v211
	v_exp_f32_e32 v167, v69
	s_waitcnt lgkmcnt(0)
	v_mfma_f32_32x32x16_bf16 v[16:31], v[64:67], v[72:75], v[16:31]
	ds_read2_b64 v[64:67], v209 offset0:12 offset1:14
	v_cvt_pk_bf16_f32 v71, v167, v165
	v_cvt_pk_bf16_f32 v69, v153, v151
	v_cvt_pk_bf16_f32 v68, v157, v155
	ds_read2_b64 v[72:75], v210 offset0:44 offset1:46
	v_cvt_pk_bf16_f32 v70, v163, v161
	s_waitcnt lgkmcnt(1)
	s_nop 0
	v_mfma_f32_32x32x16_bf16 v[48:63], v[64:67], v[68:71], v[48:63]
	v_add_f32_e32 v64, v221, v219
	v_add_f32_e32 v64, v220, v64
	v_add_f32_e32 v64, v223, v64
	v_add_f32_e32 v64, v222, v64
	v_add_f32_e32 v64, v85, v64
	v_add_f32_e32 v64, v84, v64
	v_add_f32_e32 v169, v86, v64
	s_waitcnt lgkmcnt(0)
	v_mfma_f32_32x32x16_bf16 v[16:31], v[72:75], v[68:71], v[16:31]
	ds_read_b128 v[64:67], v206 offset:5120
	ds_read_b128 v[80:83], v206 offset:5152
	s_waitcnt lgkmcnt(1)
	v_mfma_f32_32x32x16_bf16 v[64:79], v[64:67], v[100:103], 0
	s_waitcnt vmcnt(0) lgkmcnt(0)
	v_mfma_f32_32x32x16_bf16 v[64:79], v[80:83], v[108:111], v[64:79]
	ds_read_b128 v[80:83], v206 offset:7680
	ds_read_b128 v[216:219], v206 offset:7712
	ds_read2_b64 v[136:139], v209 offset1:2
	ds_read2_b64 v[132:135], v209 offset0:4 offset1:6
	s_waitcnt lgkmcnt(3)
	v_mfma_f32_32x32x16_bf16 v[80:95], v[80:83], v[100:103], 0
	s_nop 5
	v_mul_f32_e32 v154, 0x3e8293ee, v64
	v_mul_f32_e32 v156, 0x3e8293ee, v65
	s_waitcnt lgkmcnt(2)
	v_mfma_f32_32x32x16_bf16 v[80:95], v[216:219], v[108:111], v[80:95]
	s_nop 11
	v_pk_mul_f32 v[64:65], v[88:89], s[2:3] op_sel_hi:[1,0]
	s_nop 0
	v_mov_b32_e32 v88, v65
	v_mov_b32_e32 v89, v64
	v_pk_mul_f32 v[64:65], v[90:91], s[2:3] op_sel_hi:[1,0]
	s_nop 0
	v_mov_b32_e32 v90, v65
	v_mov_b32_e32 v91, v64
	v_pk_mul_f32 v[64:65], v[92:93], s[2:3] op_sel_hi:[1,0]
	s_nop 0
	v_mov_b32_e32 v92, v65
	v_mov_b32_e32 v93, v64
	v_pk_mul_f32 v[64:65], v[94:95], s[2:3] op_sel_hi:[1,0]
	s_nop 0
	v_mov_b32_e32 v94, v65
	v_mov_b32_e32 v95, v64
	v_pk_mul_f32 v[64:65], v[80:81], s[2:3] op_sel_hi:[1,0]
	s_nop 0
	v_mov_b32_e32 v80, v65
	v_mov_b32_e32 v81, v64
	v_pk_mul_f32 v[64:65], v[82:83], s[2:3] op_sel_hi:[1,0]
	s_nop 0
	v_mov_b32_e32 v82, v65
	v_mov_b32_e32 v83, v64
	v_pk_mul_f32 v[64:65], v[84:85], s[2:3] op_sel_hi:[1,0]
	s_nop 0
	v_mov_b32_e32 v84, v65
	v_mov_b32_e32 v85, v64
	v_pk_mul_f32 v[64:65], v[86:87], s[2:3] op_sel_hi:[1,0]
	s_nop 0
	v_mov_b32_e32 v86, v65
	v_mov_b32_e32 v87, v64
	v_mul_f32_e32 v160, s2, v72
	v_mul_f32_e32 v158, s2, v73
	v_max3_f32 v72, v150, v154, v156
	v_mul_f32_e32 v164, s2, v74
	v_mul_f32_e32 v162, s2, v75
	s_nop 0
	v_mul_f32_e32 v168, s2, v76
	v_mul_f32_e32 v166, s2, v77
	s_nop 0
	v_mul_f32_e32 v217, s2, v78
	v_mul_f32_e32 v216, s2, v79
	s_nop 0
	v_mul_f32_e32 v219, s2, v66
	v_mul_f32_e32 v218, s2, v67
	s_nop 0
	v_mul_f32_e32 v221, s2, v68
	v_mul_f32_e32 v220, s2, v69
	v_max3_f32 v66, v72, v219, v218
	v_mul_f32_e32 v223, s2, v70
	v_mul_f32_e32 v222, s2, v71
	v_max3_f32 v66, v66, v221, v220
	v_max3_f32 v64, v66, v223, v222
	v_max3_f32 v64, v64, v160, v158
	v_max3_f32 v64, v64, v164, v162
	v_max3_f32 v64, v64, v168, v166
	v_max3_f32 v64, v64, v217, v216
	v_max3_f32 v64, v64, v81, v80
	v_max3_f32 v64, v64, v83, v82
	v_max3_f32 v64, v64, v85, v84
	v_max3_f32 v64, v64, v87, v86
	v_max3_f32 v64, v64, v89, v88
	v_max3_f32 v64, v64, v91, v90
	v_max3_f32 v64, v64, v93, v92
	v_max3_f32 v224, v64, v95, v94
	ds_bpermute_b32 v152, v152, v224
	ds_read2_b64 v[76:79], v210 offset0:32 offset1:34
	ds_read2_b64 v[72:75], v210 offset0:36 offset1:38
	ds_read2_b64 v[68:71], v209 offset0:8 offset1:10
	ds_read2_b64 v[64:67], v210 offset0:40 offset1:42
	s_waitcnt lgkmcnt(4)
; DI float fexp2(float x) { return __builtin_amdgcn_exp2f(x); }
; #define MFMA32(a, b, c) __builtin_amdgcn_mfma_f32_32x32x16_bf16((a), (b), (c), 0, 0, 0)
; DI void pv_accum(const f32x16 (&s)[2], const bf16_t* sV, int r, int h, f32x16 (&O)[2]) {
;     ...
;       const bf16x8 pf = pack8(s[t2], s2);
; #pragma unroll
;       for (int dt = 0; dt < 2; ++dt) {
;         const bf16_t* vp = sV + (dt * 32 + r) * 68 + t2 * 32 + 16 * s2 + 4 * h;
;         const s16x4 lo = *(const s16x4*)vp, hi = *(const s16x4*)(vp + 8);
;         const bf16x8 vf = __builtin_shufflevector(lo, hi, 0, 1, 2, 3, 4, 5, 6, 7);
;         O[dt] = MFMA32(vf, pf, O[dt]);
; template <int DQK>
; DI void attn_tile_step(const bf16_t* sK, const bf16_t* sV, const bf16x8 (&qf)[DQK / 16], int k0, int qpos, int window, float sl2, float& m, float& lsum, f32x16 (&O)[2], int r, int h) {
;     ...
;       const float v = ok ? s[t2][i] * sl2 : -1e30f; s[t2][i] = v; mx = fmaxf(mx, v); }
;   mx = fmaxf(mx, __shfl_xor(mx, 32));
;   const float corr = fexp2(m - mx); m = mx; float ps = 0.f;
; #pragma unroll
;   for (int t2 = 0; t2 < 2; ++t2)
; #pragma unroll
;     for (int i = 0; i < 16; ++i) { const float pv = (s[t2][i] > -1e29f) ? fexp2(s[t2][i] - mx) : 0.f; s[t2][i] = pv; ps += pv; }
;   lsum = lsum * corr + ps;
; #pragma unroll
;   for (int dt = 0; dt < 2; ++dt)
; #pragma unroll
;     for (int i = 0; i < 16; ++i) O[dt][i] *= corr;
;   pv_accum(s, sV, r, h, O);
	v_max_f32_e32 v152, v152, v152
	v_max_f32_e32 v224, v224, v152
	v_sub_f32_e32 v225, v150, v224
	v_sub_f32_e32 v150, v156, v224
	v_exp_f32_e32 v226, v150
	v_sub_f32_e32 v152, v154, v224
	v_exp_f32_e32 v227, v152
	v_sub_f32_e32 v154, v219, v224
	v_exp_f32_e32 v219, v154
	v_sub_f32_e32 v152, v218, v224
	v_exp_f32_e32 v218, v152
	v_add_f32_e32 v150, 0, v227
	v_add_f32_e32 v150, v226, v150
	v_sub_f32_e32 v152, v220, v224
	v_exp_f32_e32 v220, v152
	s_nop 1
	v_sub_f32_e32 v154, v221, v224
	v_exp_f32_e32 v221, v154
	v_add_f32_e32 v150, v219, v150
	v_add_f32_e32 v150, v218, v150
	v_sub_f32_e32 v152, v222, v224
	v_exp_f32_e32 v222, v152
	s_nop 1
	v_sub_f32_e32 v154, v223, v224
	v_exp_f32_e32 v223, v154
	v_add_f32_e32 v150, v221, v150
	v_add_f32_e32 v150, v220, v150
	v_sub_f32_e32 v152, v158, v224
	v_exp_f32_e32 v228, v152
	s_nop 1
	v_sub_f32_e32 v154, v160, v224
	v_exp_f32_e32 v160, v154
	v_add_f32_e32 v150, v223, v150
	v_add_f32_e32 v150, v222, v150
	v_sub_f32_e32 v152, v162, v224
	v_exp_f32_e32 v162, v152
	s_nop 1
	v_sub_f32_e32 v154, v164, v224
	v_exp_f32_e32 v164, v154
	v_add_f32_e32 v150, v160, v150
	v_add_f32_e32 v150, v228, v150
	v_sub_f32_e32 v152, v166, v224
	v_exp_f32_e32 v166, v152
	s_nop 1
	v_sub_f32_e32 v154, v168, v224
	v_exp_f32_e32 v229, v154
	v_add_f32_e32 v150, v164, v150
	v_add_f32_e32 v150, v162, v150
	v_sub_f32_e32 v152, v216, v224
	v_exp_f32_e32 v216, v152
	s_nop 1
	v_sub_f32_e32 v154, v217, v224
	v_exp_f32_e32 v217, v154
	v_add_f32_e32 v150, v229, v150
	v_add_f32_e32 v150, v166, v150
	v_sub_f32_e32 v152, v80, v224
	v_exp_f32_e32 v230, v152
	s_nop 1
	v_sub_f32_e32 v154, v81, v224
	v_exp_f32_e32 v231, v154
	v_add_f32_e32 v150, v217, v150
	v_add_f32_e32 v150, v216, v150
	v_sub_f32_e32 v81, v82, v224
	v_exp_f32_e32 v232, v81
	v_add_f32_e32 v80, v231, v150
	v_sub_f32_e32 v150, v83, v224
	v_exp_f32_e32 v233, v150
	v_sub_f32_e32 v82, v85, v224
	v_sub_f32_e32 v81, v84, v224
	v_exp_f32_e32 v234, v81
	v_exp_f32_e32 v235, v82
	v_add_f32_e32 v80, v230, v80
	v_add_f32_e32 v80, v233, v80
	v_add_f32_e32 v80, v232, v80
	v_sub_f32_e32 v81, v86, v224
	v_exp_f32_e32 v158, v81
	v_sub_f32_e32 v82, v87, v224
	v_exp_f32_e32 v86, v82
	v_add_f32_e32 v80, v235, v80
	v_add_f32_e32 v80, v234, v80
	v_sub_f32_e32 v81, v89, v224
	v_exp_f32_e32 v156, v81
	v_add_f32_e32 v168, v86, v80
	v_sub_f32_e32 v80, v88, v224
	v_exp_f32_e32 v154, v80
	s_nop 0
	v_sub_f32_e32 v80, v90, v224
	v_exp_f32_e32 v150, v80
	v_sub_f32_e32 v81, v91, v224
	v_exp_f32_e32 v152, v81
	v_sub_f32_e32 v80, v93, v224
	v_exp_f32_e32 v87, v80
	v_exp_f32_e32 v80, v225
	v_sub_f32_e32 v81, v92, v224
	v_exp_f32_e32 v88, v81
	v_mov_b32_e32 v81, v142
	v_pk_mul_f32 v[46:47], v[46:47], v[80:81] op_sel_hi:[1,0]
	v_pk_mul_f32 v[44:45], v[44:45], v[80:81] op_sel_hi:[1,0]
	v_pk_mul_f32 v[42:43], v[42:43], v[80:81] op_sel_hi:[1,0]
	v_pk_mul_f32 v[40:41], v[40:41], v[80:81] op_sel_hi:[1,0]
	v_pk_mul_f32 v[38:39], v[38:39], v[80:81] op_sel_hi:[1,0]
	v_pk_mul_f32 v[36:37], v[36:37], v[80:81] op_sel_hi:[1,0]
	v_pk_mul_f32 v[34:35], v[34:35], v[80:81] op_sel_hi:[1,0]
	v_pk_mul_f32 v[32:33], v[32:33], v[80:81] op_sel_hi:[1,0]
	v_cvt_pk_bf16_f32 v85, v223, v222
	v_cvt_pk_bf16_f32 v84, v221, v220
	v_cvt_pk_bf16_f32 v83, v219, v218
	v_cvt_pk_bf16_f32 v82, v227, v226
	v_pk_mul_f32 v[14:15], v[14:15], v[80:81] op_sel_hi:[1,0]
	v_pk_mul_f32 v[12:13], v[12:13], v[80:81] op_sel_hi:[1,0]
	v_mfma_f32_32x32x16_bf16 v[32:47], v[136:139], v[82:85], v[32:47]
	v_mul_f32_e64 v10, v10, v80
	v_mul_f32_e64 v11, v11, v80
	v_mul_f32_e64 v8, v8, v80
	v_mul_f32_e64 v9, v9, v80
	v_mul_f32_e64 v6, v6, v80
	v_mul_f32_e64 v7, v7, v80
	v_pk_mul_f32 v[4:5], v[4:5], v[80:81] op_sel_hi:[1,0]
	v_pk_mul_f32 v[2:3], v[2:3], v[80:81] op_sel_hi:[1,0]
	v_pk_mul_f32 v[0:1], v[0:1], v[80:81] op_sel_hi:[1,0]
	s_waitcnt lgkmcnt(3)
	s_nop 0
	v_mfma_f32_32x32x16_bf16 v[0:15], v[76:79], v[82:85], v[0:15]
	v_cvt_pk_bf16_f32 v79, v217, v216
	v_cvt_pk_bf16_f32 v78, v229, v166
	v_cvt_pk_bf16_f32 v77, v164, v162
	v_cvt_pk_bf16_f32 v76, v160, v228
	v_sub_f32_e32 v83, v94, v224
	v_sub_f32_e32 v82, v95, v224
	v_mfma_f32_32x32x16_bf16 v[32:47], v[132:135], v[76:79], v[32:47]
	v_exp_f32_e32 v164, v83
	v_exp_f32_e32 v166, v82
	v_mov_b32_e32 v160, v88
	s_nop 1
	v_mov_b32_e32 v162, v87
	s_waitcnt lgkmcnt(2)
	v_mfma_f32_32x32x16_bf16 v[0:15], v[72:75], v[76:79], v[0:15]
	v_cvt_pk_bf16_f32 v75, v86, v158
	v_cvt_pk_bf16_f32 v74, v235, v234
	v_cvt_pk_bf16_f32 v73, v233, v232
	v_cvt_pk_bf16_f32 v72, v231, v230
	s_waitcnt lgkmcnt(1)
	s_nop 0
	v_mfma_f32_32x32x16_bf16 v[32:47], v[68:71], v[72:75], v[32:47]
	v_add_f32_e64 v68, v158, v168
	v_add_f32_e64 v69, v159, v169
	v_pk_add_f32 v[68:69], v[156:157], v[68:69]
	v_pk_add_f32 v[76:77], v[154:155], v[68:69]
	s_waitcnt lgkmcnt(0)
	v_mfma_f32_32x32x16_bf16 v[0:15], v[64:67], v[72:75], v[0:15]
	ds_read2_b64 v[64:67], v209 offset0:12 offset1:14
	v_cvt_pk_bf16_f32 v71, v166, v164
	v_cvt_pk_bf16_f32 v69, v152, v150
	v_cvt_pk_bf16_f32 v68, v156, v154
	ds_read2_b64 v[72:75], v210 offset0:44 offset1:46
	v_cvt_pk_bf16_f32 v70, v162, v160
	s_waitcnt lgkmcnt(1)
	s_nop 0
	v_mfma_f32_32x32x16_bf16 v[32:47], v[64:67], v[68:71], v[32:47]
	v_add_f32_e64 v64, v152, v76
	v_add_f32_e64 v65, v153, v77
	v_add_f32_e64 v64, v150, v64
	v_add_f32_e64 v65, v151, v65
	v_add_f32_e64 v64, v162, v64
	v_add_f32_e64 v65, v163, v65
	v_pk_add_f32 v[64:65], v[160:161], v[64:65]
	s_waitcnt lgkmcnt(0)
	v_mfma_f32_32x32x16_bf16 v[0:15], v[72:75], v[68:71], v[0:15]
	v_add_f32_e64 v64, v166, v64
	v_add_f32_e64 v65, v167, v65
	v_add_f32_e64 v64, v164, v64
	v_add_f32_e64 v65, v165, v65
	v_fma_f32 v146, v146, v80, v64
	v_fma_f32 v147, v147, v81, v65
	v_mov_b32_e32 v151, v211
	v_mov_b32_e32 v150, v224
	s_branch .LBB0_536
